# v22 + SSE touch before P5 + P0 XN trip rotation + barrier non-leaders poll the cross-XCD release word
# speedup vs baseline: 1.0271x; 1.0001x over previous
.LBB0_60:
	s_or_b64 exec, exec, s[2:3]
	s_add_i32 s0, s0, 32
	s_and_b32 s0, s0, 0x7ff
	s_cmpk_gt_i32 s0, 0x101f
	s_cbranch_scc1 .LBB0_63
	s_lshl_b32 s0, s0, 2
	v_mov_b32_e32 v71, 0
	s_lshl_b32 s1, s71, 5
	v_lshl_add_u64 v[74:75], s[90:91], 0, v[70:71]
	s_ashr_i32 s16, s0, 31
	s_ashr_i32 s17, s1, 31
	v_lshlrev_b32_e32 v70, 4, v190
	s_movk_i32 s20, 0x1000
	s_movk_i32 s21, 0x2000
	s_movk_i32 s22, 0x3000
	v_mov_b32_e32 v80, 0x358637bd
	s_mov_b32 s23, 0xf800000
	v_mov_b32_e32 v81, 0x260
	v_lshlrev_b32_e32 v76, 3, v190
	v_mov_b32_e32 v77, v71
	s_movk_i32 s24, 0x7fff
	s_mov_b32 s25, 0xffff0000

.LBB0_113:
	s_or_b64 exec, exec, s[8:9]
	v_cvt_f32_u32_e32 v6, v4
	s_waitcnt vmcnt(0)
	v_readfirstlane_b32 s0, v5
	v_sub_u32_e32 v5, 0, v4
	v_rcp_iflag_f32_e32 v6, v6
	v_add_u32_e32 v7, s0, v3
	v_mul_f32_e32 v6, 0x4f7ffffe, v6
	v_cvt_u32_f32_e32 v6, v6
	v_mul_lo_u32 v3, v5, v6
	v_mul_hi_u32 v3, v6, v3
	v_add_u32_e32 v3, v6, v3
	v_mul_hi_u32 v3, v7, v3
	v_mul_lo_u32 v5, v3, v4
	v_sub_u32_e32 v5, v7, v5
	v_add_u32_e32 v6, 1, v3
	v_cmp_ge_u32_e32 vcc, v5, v4
	s_nop 1
	v_cndmask_b32_e32 v3, v3, v6, vcc
	v_sub_u32_e32 v6, v5, v4
	v_cndmask_b32_e32 v5, v5, v6, vcc
	v_add_u32_e32 v6, 1, v3
	v_cmp_ge_u32_e32 vcc, v5, v4
	v_add_u32_e32 v5, 1, v7
	s_nop 0
	v_cndmask_b32_e32 v3, v3, v6, vcc
	v_mul_lo_u32 v6, v4, v3
	v_add_u32_e32 v4, v6, v4
	v_cmp_ne_u32_e32 vcc, v5, v4
	s_and_saveexec_b64 s[0:1], vcc
	s_xor_b64 s[6:7], exec, s[0:1]
	s_cbranch_execz .LBB0_127
	s_waitcnt lgkmcnt(0)
	v_readlane_b32 s10, v251, 38
	v_readlane_b32 s11, v251, 39
	v_mov_b32_e32 v2, 0
	s_nop 3
	s_add_u32 s10, s10, 0x3500
	s_addc_u32 s11, s11, 0
	global_load_dword v2, v2, s[10:11] sc1
	s_waitcnt vmcnt(0)
	v_cmp_eq_u32_e32 vcc, v2, v3
	s_and_saveexec_b64 s[8:9], vcc
	s_cbranch_execz .LBB0_126
	s_mov_b32 s0, 1
	s_mov_b64 s[12:13], 0
	v_mov_b32_e32 v2, 0
	s_branch .LBB0_117
